# PEER per-token fp8 quantisation batched across the wave's tokens + LN2 wave sums via DPP/permlane instead of ds_bpermute
# speedup vs baseline: 1.0163x; 1.0031x over previous
; __device__ __forceinline__ void ph_peer(const P& p, int l, int nrows, char* smem, int dryc) {
;     ...
;       for (int tk = 0; tk < n; tk++) {
;         int row = rowb + wave * n + tk;
;         float xv[16];
;         u32x4 a = *(const u32x4*)(xm + (size_t)row * 1024 + lane * 16);
;         u32x4 bq = *(const u32x4*)(xm + (size_t)row * 1024 + lane * 16 + 8);
;         unpack8(a, xv); unpack8(bq, xv + 8);
;         float am = 0.f;
; #pragma unroll
;         for (int i = 0; i < 16; i++) am = fmaxf(am, fabsf(xv[i]));
;         am = fmaxf(am, __shfl_xor(am, 1, 64)); am = fmaxf(am, __shfl_xor(am, 2, 64)); am = fmaxf(am, __shfl_xor(am, 4, 64));
;         am = fmaxf(am, __shfl_xor(am, 8, 64)); am = fmaxf(am, __shfl_xor(am, 16, 64)); am = fmaxf(am, __shfl_xor(am, 32, 64));
;         float qs = am > 0.f ? 240.f / am : 1.f;
;         if (lane == 0) sQinv[wave * 4 + tk] = am > 0.f ? am * (1.f / 240.f) : 1.f;
.LBB0_697:
	s_or_b64 exec, exec, s[0:1]
	s_waitcnt vmcnt(15)
	v_and_b32_e32 v3, 64, v212
	v_xor_b32_e32 v2, 1, v212
	v_add_u32_e32 v3, 64, v3
	v_cmp_lt_i32_e32 vcc, v2, v3
	v_ashrrev_i32_e32 v159, 31, v158
	v_lshlrev_b64 v[0:1], 11, v[158:159]
	v_cndmask_b32_e32 v2, v212, v2, vcc
	v_lshlrev_b32_e32 v155, 2, v2
	v_xor_b32_e32 v2, 2, v212
	v_cmp_lt_i32_e32 vcc, v2, v3
	v_mov_b32_e32 v251, 0x68
	v_mov_b32_e32 v215, 0x78
	v_cndmask_b32_e32 v2, v212, v2, vcc
	v_lshlrev_b32_e32 v159, 2, v2
	v_xor_b32_e32 v2, 4, v212
	v_cmp_lt_i32_e32 vcc, v2, v3
	v_lshl_add_u64 v[0:1], v[156:157], 0, v[0:1]
	s_mov_b32 s14, s75
	v_cndmask_b32_e32 v2, v212, v2, vcc
	v_lshlrev_b32_e32 v244, 2, v2
	v_xor_b32_e32 v2, 8, v212
	v_cmp_lt_i32_e32 vcc, v2, v3
	s_waitcnt lgkmcnt(0)
	s_barrier
	v_cndmask_b32_e32 v2, v212, v2, vcc
	v_lshlrev_b32_e32 v245, 2, v2
	v_xor_b32_e32 v2, 16, v212
	v_cmp_lt_i32_e32 vcc, v2, v3
	v_mov_b32 v131, 0
	s_nop 1
	v_cndmask_b32_e32 v2, v212, v2, vcc
	v_lshlrev_b32_e32 v246, 2, v2
	v_xor_b32_e32 v2, 32, v212
	v_cmp_lt_i32_e32 vcc, v2, v3
	v_mov_b32_e32 v3, v239
	s_nop 0
	v_cndmask_b32_e32 v2, v212, v2, vcc
	v_lshlrev_b32_e32 v247, 2, v2
	v_mov_b32_e32 v2, v240
	s_cmp_eq_u32 s14, 4
	s_cbranch_scc0 .Lqn3
.Lqn4:
	s_mov_b64 s[0:1], 0x1000
	v_lshl_add_u64 v[26:27], v[0:1], 0, s[0:1]
	global_load_dwordx4 v[32:35], v[0:1], off
	global_load_dwordx4 v[36:39], v[0:1], off offset:16
	global_load_dwordx4 v[40:43], v[0:1], off offset:2048
	global_load_dwordx4 v[44:47], v[0:1], off offset:2064
	global_load_dwordx4 v[48:51], v[26:27], off
	global_load_dwordx4 v[52:55], v[26:27], off offset:16
	global_load_dwordx4 v[56:59], v[26:27], off offset:2048
	global_load_dwordx4 v[60:63], v[26:27], off offset:2064
	s_mov_b32 s12, 0x7fff7fff
	s_mov_b32 s15, 0x43700000
	s_waitcnt vmcnt(6)
	v_and_b32_e32 v64, s12, v32
	v_and_b32_e32 v68, s12, v33
	v_pk_max_u16 v64, v64, v68
	v_and_b32_e32 v68, s12, v34
	v_pk_max_u16 v64, v64, v68
	v_and_b32_e32 v68, s12, v35
	v_pk_max_u16 v64, v64, v68
	v_and_b32_e32 v68, s12, v36
	v_pk_max_u16 v64, v64, v68
	v_and_b32_e32 v68, s12, v37
	v_pk_max_u16 v64, v64, v68
	v_and_b32_e32 v68, s12, v38
	v_pk_max_u16 v64, v64, v68
	v_and_b32_e32 v68, s12, v39
	v_pk_max_u16 v64, v64, v68
	v_lshlrev_b32_e32 v68, 16, v64
	v_and_b32_e32 v64, 0xffff0000, v64
	v_max_u32_e32 v64, v64, v68
	s_waitcnt vmcnt(4)
	v_and_b32_e32 v65, s12, v40
	v_and_b32_e32 v69, s12, v41
	v_pk_max_u16 v65, v65, v69
	v_and_b32_e32 v69, s12, v42
	v_pk_max_u16 v65, v65, v69
	v_and_b32_e32 v69, s12, v43
	v_pk_max_u16 v65, v65, v69
	v_and_b32_e32 v69, s12, v44
	v_pk_max_u16 v65, v65, v69
	v_and_b32_e32 v69, s12, v45
	v_pk_max_u16 v65, v65, v69
	v_and_b32_e32 v69, s12, v46
	v_pk_max_u16 v65, v65, v69
	v_and_b32_e32 v69, s12, v47
	v_pk_max_u16 v65, v65, v69
	v_lshlrev_b32_e32 v69, 16, v65
	v_and_b32_e32 v65, 0xffff0000, v65
	v_max_u32_e32 v65, v65, v69
	s_waitcnt vmcnt(2)
	v_and_b32_e32 v66, s12, v48
	v_and_b32_e32 v70, s12, v49
	v_pk_max_u16 v66, v66, v70
	v_and_b32_e32 v70, s12, v50
	v_pk_max_u16 v66, v66, v70
	v_and_b32_e32 v70, s12, v51
	v_pk_max_u16 v66, v66, v70
	v_and_b32_e32 v70, s12, v52
	v_pk_max_u16 v66, v66, v70
	v_and_b32_e32 v70, s12, v53
	v_pk_max_u16 v66, v66, v70
	v_and_b32_e32 v70, s12, v54
	v_pk_max_u16 v66, v66, v70
	v_and_b32_e32 v70, s12, v55
	v_pk_max_u16 v66, v66, v70
	v_lshlrev_b32_e32 v70, 16, v66
	v_and_b32_e32 v66, 0xffff0000, v66
	v_max_u32_e32 v66, v66, v70
	s_waitcnt vmcnt(0)
	v_and_b32_e32 v67, s12, v56
	v_and_b32_e32 v71, s12, v57
	v_pk_max_u16 v67, v67, v71
	v_and_b32_e32 v71, s12, v58
	v_pk_max_u16 v67, v67, v71
	v_and_b32_e32 v71, s12, v59
	v_pk_max_u16 v67, v67, v71
	v_and_b32_e32 v71, s12, v60
	v_pk_max_u16 v67, v67, v71
	v_and_b32_e32 v71, s12, v61
	v_pk_max_u16 v67, v67, v71
	v_and_b32_e32 v71, s12, v62
	v_pk_max_u16 v67, v67, v71
	v_and_b32_e32 v71, s12, v63
	v_pk_max_u16 v67, v67, v71
	v_lshlrev_b32_e32 v71, 16, v67
	v_and_b32_e32 v67, 0xffff0000, v67
	v_max_u32_e32 v67, v67, v71
	ds_bpermute_b32 v68, v155, v64
	ds_bpermute_b32 v69, v155, v65
	ds_bpermute_b32 v70, v155, v66
	ds_bpermute_b32 v71, v155, v67
	s_waitcnt lgkmcnt(3)
	v_max_u32_e32 v64, v64, v68
	s_waitcnt lgkmcnt(2)
	v_max_u32_e32 v65, v65, v69
	s_waitcnt lgkmcnt(1)
	v_max_u32_e32 v66, v66, v70
	s_waitcnt lgkmcnt(0)
	v_max_u32_e32 v67, v67, v71
	ds_bpermute_b32 v68, v159, v64
	ds_bpermute_b32 v69, v159, v65
	ds_bpermute_b32 v70, v159, v66
	ds_bpermute_b32 v71, v159, v67
	s_waitcnt lgkmcnt(3)
	v_max_u32_e32 v64, v64, v68
	s_waitcnt lgkmcnt(2)
	v_max_u32_e32 v65, v65, v69
	s_waitcnt lgkmcnt(1)
	v_max_u32_e32 v66, v66, v70
	s_waitcnt lgkmcnt(0)
	v_max_u32_e32 v67, v67, v71
	ds_bpermute_b32 v68, v244, v64
	ds_bpermute_b32 v69, v244, v65
	ds_bpermute_b32 v70, v244, v66
	ds_bpermute_b32 v71, v244, v67
	s_waitcnt lgkmcnt(3)
	v_max_u32_e32 v64, v64, v68
	s_waitcnt lgkmcnt(2)
	v_max_u32_e32 v65, v65, v69
	s_waitcnt lgkmcnt(1)
	v_max_u32_e32 v66, v66, v70
	s_waitcnt lgkmcnt(0)
	v_max_u32_e32 v67, v67, v71
	ds_bpermute_b32 v68, v245, v64
	ds_bpermute_b32 v69, v245, v65
	ds_bpermute_b32 v70, v245, v66
	ds_bpermute_b32 v71, v245, v67
	s_waitcnt lgkmcnt(3)
	v_max_u32_e32 v64, v64, v68
	s_waitcnt lgkmcnt(2)
	v_max_u32_e32 v65, v65, v69
	s_waitcnt lgkmcnt(1)
	v_max_u32_e32 v66, v66, v70
	s_waitcnt lgkmcnt(0)
	v_max_u32_e32 v67, v67, v71
	ds_bpermute_b32 v68, v246, v64
	ds_bpermute_b32 v69, v246, v65
	ds_bpermute_b32 v70, v246, v66
	ds_bpermute_b32 v71, v246, v67
	s_waitcnt lgkmcnt(3)
	v_max_u32_e32 v64, v64, v68
	s_waitcnt lgkmcnt(2)
	v_max_u32_e32 v65, v65, v69
	s_waitcnt lgkmcnt(1)
	v_max_u32_e32 v66, v66, v70
	s_waitcnt lgkmcnt(0)
; __device__ __forceinline__ void ph_peer(const P& p, int l, int nrows, char* smem, int dryc) {
;     ...
;         am = fmaxf(am, __shfl_xor(am, 1, 64)); am = fmaxf(am, __shfl_xor(am, 2, 64)); am = fmaxf(am, __shfl_xor(am, 4, 64));
;         am = fmaxf(am, __shfl_xor(am, 8, 64)); am = fmaxf(am, __shfl_xor(am, 16, 64)); am = fmaxf(am, __shfl_xor(am, 32, 64));
;         float qs = am > 0.f ? 240.f / am : 1.f;
;         if (lane == 0) sQinv[wave * 4 + tk] = am > 0.f ? am * (1.f / 240.f) : 1.f;
;         u32x4 x8; int w;
; #pragma unroll
;         for (int i = 0; i < 4; i++) {
;           w = 0;
;           w = __builtin_amdgcn_cvt_pk_fp8_f32(xv[i * 4 + 0] * qs, xv[i * 4 + 1] * qs, w, false);
;           w = __builtin_amdgcn_cvt_pk_fp8_f32(xv[i * 4 + 2] * qs, xv[i * 4 + 3] * qs, w, true);
;           x8[i] = (u32)w;
;         }
;         *(u32x4*)(sX8 + (wave * 4 + tk) * 1024 + lane * 16) = x8;
	v_max_u32_e32 v67, v67, v71
	ds_bpermute_b32 v68, v247, v64
	ds_bpermute_b32 v69, v247, v65
	ds_bpermute_b32 v70, v247, v66
	ds_bpermute_b32 v71, v247, v67
	s_waitcnt lgkmcnt(3)
	v_max_u32_e32 v64, v64, v68
	s_waitcnt lgkmcnt(2)
	v_max_u32_e32 v65, v65, v69
	s_waitcnt lgkmcnt(1)
	v_max_u32_e32 v66, v66, v70
	s_waitcnt lgkmcnt(0)
	v_max_u32_e32 v67, v67, v71
	v_cmp_lt_f32_e64 s[12:13], 0, v64
	v_div_scale_f32 v72, s[0:1], v64, v64, s15
	v_rcp_f32_e32 v73, v72
	v_div_scale_f32 v74, vcc, s15, v64, s15
	v_fma_f32 v75, -v72, v73, 1.0
	v_fmac_f32_e32 v73, v75, v73
	v_mul_f32_e32 v75, v74, v73
	v_fma_f32 v76, -v72, v75, v74
	v_fmac_f32_e32 v75, v76, v73
	v_fma_f32 v72, -v72, v75, v74
	v_div_fmas_f32 v72, v72, v73, v75
	v_div_fixup_f32 v72, v72, v64, s15
	v_cndmask_b32_e64 v77, 1.0, v72, s[12:13]
	v_mul_f32_e32 v78, 0x3b888889, v64
	v_cndmask_b32_e64 v78, 1.0, v78, s[12:13]
	v_lshlrev_b32_e32 v68, 16, v32
	v_and_b32_e32 v69, 0xffff0000, v32
	v_lshlrev_b32_e32 v70, 16, v33
	v_and_b32_e32 v71, 0xffff0000, v33
	v_mul_f32_e32 v68, v77, v68
	v_mul_f32_e32 v69, v77, v69
	v_mul_f32_e32 v70, v77, v70
	v_mul_f32_e32 v71, v77, v71
	v_cvt_pk_fp8_f32 v84, v68, v69
	v_cvt_pk_fp8_f32 v84, v70, v71 op_sel:[0,0,1]
	v_lshlrev_b32_e32 v68, 16, v34
	v_and_b32_e32 v69, 0xffff0000, v34
	v_lshlrev_b32_e32 v70, 16, v35
	v_and_b32_e32 v71, 0xffff0000, v35
	v_mul_f32_e32 v68, v77, v68
	v_mul_f32_e32 v69, v77, v69
	v_mul_f32_e32 v70, v77, v70
	v_mul_f32_e32 v71, v77, v71
	v_cvt_pk_fp8_f32 v85, v68, v69
	v_cvt_pk_fp8_f32 v85, v70, v71 op_sel:[0,0,1]
	v_lshlrev_b32_e32 v68, 16, v36
	v_and_b32_e32 v69, 0xffff0000, v36
	v_lshlrev_b32_e32 v70, 16, v37
	v_and_b32_e32 v71, 0xffff0000, v37
	v_mul_f32_e32 v68, v77, v68
	v_mul_f32_e32 v69, v77, v69
	v_mul_f32_e32 v70, v77, v70
	v_mul_f32_e32 v71, v77, v71
	v_cvt_pk_fp8_f32 v86, v68, v69
	v_cvt_pk_fp8_f32 v86, v70, v71 op_sel:[0,0,1]
	v_lshlrev_b32_e32 v68, 16, v38
	v_and_b32_e32 v69, 0xffff0000, v38
	v_lshlrev_b32_e32 v70, 16, v39
	v_and_b32_e32 v71, 0xffff0000, v39
	v_mul_f32_e32 v68, v77, v68
	v_mul_f32_e32 v69, v77, v69
	v_mul_f32_e32 v70, v77, v70
	v_mul_f32_e32 v71, v77, v71
	v_cvt_pk_fp8_f32 v87, v68, v69
	v_cvt_pk_fp8_f32 v87, v70, v71 op_sel:[0,0,1]
	ds_write_b128 v2, v[84:87]
	s_and_saveexec_b64 s[0:1], s[10:11]
	ds_write_b32 v3, v78
	s_mov_b64 exec, s[0:1]
	v_cmp_lt_f32_e64 s[12:13], 0, v65
	v_div_scale_f32 v72, s[0:1], v65, v65, s15
	v_rcp_f32_e32 v73, v72
	v_div_scale_f32 v74, vcc, s15, v65, s15
	v_fma_f32 v75, -v72, v73, 1.0
	v_fmac_f32_e32 v73, v75, v73
	v_mul_f32_e32 v75, v74, v73
	v_fma_f32 v76, -v72, v75, v74
	v_fmac_f32_e32 v75, v76, v73
	v_fma_f32 v72, -v72, v75, v74
	v_div_fmas_f32 v72, v72, v73, v75
	v_div_fixup_f32 v72, v72, v65, s15
	v_cndmask_b32_e64 v77, 1.0, v72, s[12:13]
	v_mul_f32_e32 v78, 0x3b888889, v65
	v_cndmask_b32_e64 v78, 1.0, v78, s[12:13]
	v_lshlrev_b32_e32 v68, 16, v40
	v_and_b32_e32 v69, 0xffff0000, v40
	v_lshlrev_b32_e32 v70, 16, v41
	v_and_b32_e32 v71, 0xffff0000, v41
	v_mul_f32_e32 v68, v77, v68
	v_mul_f32_e32 v69, v77, v69
	v_mul_f32_e32 v70, v77, v70
	v_mul_f32_e32 v71, v77, v71
	v_cvt_pk_fp8_f32 v88, v68, v69
	v_cvt_pk_fp8_f32 v88, v70, v71 op_sel:[0,0,1]
	v_lshlrev_b32_e32 v68, 16, v42
	v_and_b32_e32 v69, 0xffff0000, v42
	v_lshlrev_b32_e32 v70, 16, v43
	v_and_b32_e32 v71, 0xffff0000, v43
	v_mul_f32_e32 v68, v77, v68
	v_mul_f32_e32 v69, v77, v69
	v_mul_f32_e32 v70, v77, v70
	v_mul_f32_e32 v71, v77, v71
	v_cvt_pk_fp8_f32 v89, v68, v69
	v_cvt_pk_fp8_f32 v89, v70, v71 op_sel:[0,0,1]
	v_lshlrev_b32_e32 v68, 16, v44
	v_and_b32_e32 v69, 0xffff0000, v44
	v_lshlrev_b32_e32 v70, 16, v45
	v_and_b32_e32 v71, 0xffff0000, v45
	v_mul_f32_e32 v68, v77, v68
	v_mul_f32_e32 v69, v77, v69
	v_mul_f32_e32 v70, v77, v70
	v_mul_f32_e32 v71, v77, v71
	v_cvt_pk_fp8_f32 v90, v68, v69
	v_cvt_pk_fp8_f32 v90, v70, v71 op_sel:[0,0,1]
	v_lshlrev_b32_e32 v68, 16, v46
	v_and_b32_e32 v69, 0xffff0000, v46
	v_lshlrev_b32_e32 v70, 16, v47
	v_and_b32_e32 v71, 0xffff0000, v47
	v_mul_f32_e32 v68, v77, v68
	v_mul_f32_e32 v69, v77, v69
	v_mul_f32_e32 v70, v77, v70
	v_mul_f32_e32 v71, v77, v71
	v_cvt_pk_fp8_f32 v91, v68, v69
	v_cvt_pk_fp8_f32 v91, v70, v71 op_sel:[0,0,1]
	ds_write_b128 v2, v[88:91] offset:1024
	s_and_saveexec_b64 s[0:1], s[10:11]
	ds_write_b32 v3, v78 offset:4
	s_mov_b64 exec, s[0:1]
	v_cmp_lt_f32_e64 s[12:13], 0, v66
	v_div_scale_f32 v72, s[0:1], v66, v66, s15
	v_rcp_f32_e32 v73, v72
	v_div_scale_f32 v74, vcc, s15, v66, s15
	v_fma_f32 v75, -v72, v73, 1.0
	v_fmac_f32_e32 v73, v75, v73
	v_mul_f32_e32 v75, v74, v73
	v_fma_f32 v76, -v72, v75, v74
	v_fmac_f32_e32 v75, v76, v73
	v_fma_f32 v72, -v72, v75, v74
	v_div_fmas_f32 v72, v72, v73, v75
	v_div_fixup_f32 v72, v72, v66, s15
	v_cndmask_b32_e64 v77, 1.0, v72, s[12:13]
	v_mul_f32_e32 v78, 0x3b888889, v66
	v_cndmask_b32_e64 v78, 1.0, v78, s[12:13]
	v_lshlrev_b32_e32 v68, 16, v48
	v_and_b32_e32 v69, 0xffff0000, v48
	v_lshlrev_b32_e32 v70, 16, v49
	v_and_b32_e32 v71, 0xffff0000, v49
	v_mul_f32_e32 v68, v77, v68
	v_mul_f32_e32 v69, v77, v69
	v_mul_f32_e32 v70, v77, v70
	v_mul_f32_e32 v71, v77, v71
	v_cvt_pk_fp8_f32 v92, v68, v69
	v_cvt_pk_fp8_f32 v92, v70, v71 op_sel:[0,0,1]
	v_lshlrev_b32_e32 v68, 16, v50
	v_and_b32_e32 v69, 0xffff0000, v50
	v_lshlrev_b32_e32 v70, 16, v51
	v_and_b32_e32 v71, 0xffff0000, v51
	v_mul_f32_e32 v68, v77, v68
	v_mul_f32_e32 v69, v77, v69
	v_mul_f32_e32 v70, v77, v70
	v_mul_f32_e32 v71, v77, v71
	v_cvt_pk_fp8_f32 v93, v68, v69
	v_cvt_pk_fp8_f32 v93, v70, v71 op_sel:[0,0,1]
	v_lshlrev_b32_e32 v68, 16, v52
	v_and_b32_e32 v69, 0xffff0000, v52
	v_lshlrev_b32_e32 v70, 16, v53
	v_and_b32_e32 v71, 0xffff0000, v53
	v_mul_f32_e32 v68, v77, v68
; __device__ __forceinline__ void ph_peer(const P& p, int l, int nrows, char* smem, int dryc) {
;     ...
;         u32x4 a = *(const u32x4*)(xm + (size_t)row * 1024 + lane * 16);
;         u32x4 bq = *(const u32x4*)(xm + (size_t)row * 1024 + lane * 16 + 8);
;         unpack8(a, xv); unpack8(bq, xv + 8);
;         float am = 0.f;
; #pragma unroll
;         for (int i = 0; i < 16; i++) am = fmaxf(am, fabsf(xv[i]));
;         am = fmaxf(am, __shfl_xor(am, 1, 64)); am = fmaxf(am, __shfl_xor(am, 2, 64)); am = fmaxf(am, __shfl_xor(am, 4, 64));
;         am = fmaxf(am, __shfl_xor(am, 8, 64)); am = fmaxf(am, __shfl_xor(am, 16, 64)); am = fmaxf(am, __shfl_xor(am, 32, 64));
;         float qs = am > 0.f ? 240.f / am : 1.f;
;         if (lane == 0) sQinv[wave * 4 + tk] = am > 0.f ? am * (1.f / 240.f) : 1.f;
;         u32x4 x8; int w;
; #pragma unroll
;         for (int i = 0; i < 4; i++) {
;           w = 0;
;           w = __builtin_amdgcn_cvt_pk_fp8_f32(xv[i * 4 + 0] * qs, xv[i * 4 + 1] * qs, w, false);
;           w = __builtin_amdgcn_cvt_pk_fp8_f32(xv[i * 4 + 2] * qs, xv[i * 4 + 3] * qs, w, true);
;           x8[i] = (u32)w;
;         }
;         *(u32x4*)(sX8 + (wave * 4 + tk) * 1024 + lane * 16) = x8;
	v_mul_f32_e32 v69, v77, v69
	v_mul_f32_e32 v70, v77, v70
	v_mul_f32_e32 v71, v77, v71
	v_cvt_pk_fp8_f32 v94, v68, v69
	v_cvt_pk_fp8_f32 v94, v70, v71 op_sel:[0,0,1]
	v_lshlrev_b32_e32 v68, 16, v54
	v_and_b32_e32 v69, 0xffff0000, v54
	v_lshlrev_b32_e32 v70, 16, v55
	v_and_b32_e32 v71, 0xffff0000, v55
	v_mul_f32_e32 v68, v77, v68
	v_mul_f32_e32 v69, v77, v69
	v_mul_f32_e32 v70, v77, v70
	v_mul_f32_e32 v71, v77, v71
	v_cvt_pk_fp8_f32 v95, v68, v69
	v_cvt_pk_fp8_f32 v95, v70, v71 op_sel:[0,0,1]
	ds_write_b128 v2, v[92:95] offset:2048
	s_and_saveexec_b64 s[0:1], s[10:11]
	ds_write_b32 v3, v78 offset:8
	s_mov_b64 exec, s[0:1]
	v_cmp_lt_f32_e64 s[12:13], 0, v67
	v_div_scale_f32 v72, s[0:1], v67, v67, s15
	v_rcp_f32_e32 v73, v72
	v_div_scale_f32 v74, vcc, s15, v67, s15
	v_fma_f32 v75, -v72, v73, 1.0
	v_fmac_f32_e32 v73, v75, v73
	v_mul_f32_e32 v75, v74, v73
	v_fma_f32 v76, -v72, v75, v74
	v_fmac_f32_e32 v75, v76, v73
	v_fma_f32 v72, -v72, v75, v74
	v_div_fmas_f32 v72, v72, v73, v75
	v_div_fixup_f32 v72, v72, v67, s15
	v_cndmask_b32_e64 v77, 1.0, v72, s[12:13]
	v_mul_f32_e32 v78, 0x3b888889, v67
	v_cndmask_b32_e64 v78, 1.0, v78, s[12:13]
	v_lshlrev_b32_e32 v68, 16, v56
	v_and_b32_e32 v69, 0xffff0000, v56
	v_lshlrev_b32_e32 v70, 16, v57
	v_and_b32_e32 v71, 0xffff0000, v57
	v_mul_f32_e32 v68, v77, v68
	v_mul_f32_e32 v69, v77, v69
	v_mul_f32_e32 v70, v77, v70
	v_mul_f32_e32 v71, v77, v71
	v_cvt_pk_fp8_f32 v96, v68, v69
	v_cvt_pk_fp8_f32 v96, v70, v71 op_sel:[0,0,1]
	v_lshlrev_b32_e32 v68, 16, v58
	v_and_b32_e32 v69, 0xffff0000, v58
	v_lshlrev_b32_e32 v70, 16, v59
	v_and_b32_e32 v71, 0xffff0000, v59
	v_mul_f32_e32 v68, v77, v68
	v_mul_f32_e32 v69, v77, v69
	v_mul_f32_e32 v70, v77, v70
	v_mul_f32_e32 v71, v77, v71
	v_cvt_pk_fp8_f32 v97, v68, v69
	v_cvt_pk_fp8_f32 v97, v70, v71 op_sel:[0,0,1]
	v_lshlrev_b32_e32 v68, 16, v60
	v_and_b32_e32 v69, 0xffff0000, v60
	v_lshlrev_b32_e32 v70, 16, v61
	v_and_b32_e32 v71, 0xffff0000, v61
	v_mul_f32_e32 v68, v77, v68
	v_mul_f32_e32 v69, v77, v69
	v_mul_f32_e32 v70, v77, v70
	v_mul_f32_e32 v71, v77, v71
	v_cvt_pk_fp8_f32 v98, v68, v69
	v_cvt_pk_fp8_f32 v98, v70, v71 op_sel:[0,0,1]
	v_lshlrev_b32_e32 v68, 16, v62
	v_and_b32_e32 v69, 0xffff0000, v62
	v_lshlrev_b32_e32 v70, 16, v63
	v_and_b32_e32 v71, 0xffff0000, v63
	v_mul_f32_e32 v68, v77, v68
	v_mul_f32_e32 v69, v77, v69
	v_mul_f32_e32 v70, v77, v70
	v_mul_f32_e32 v71, v77, v71
	v_cvt_pk_fp8_f32 v99, v68, v69
	v_cvt_pk_fp8_f32 v99, v70, v71 op_sel:[0,0,1]
	ds_write_b128 v2, v[96:99] offset:3072
	s_and_saveexec_b64 s[0:1], s[10:11]
	ds_write_b32 v3, v78 offset:12
	s_mov_b64 exec, s[0:1]
	s_branch .LBB0_701
.Lqn3:
	s_mov_b64 s[0:1], 0x1000
	v_lshl_add_u64 v[26:27], v[0:1], 0, s[0:1]
	global_load_dwordx4 v[32:35], v[0:1], off
	global_load_dwordx4 v[36:39], v[0:1], off offset:16
	global_load_dwordx4 v[40:43], v[0:1], off offset:2048
	global_load_dwordx4 v[44:47], v[0:1], off offset:2064
	global_load_dwordx4 v[48:51], v[26:27], off
	global_load_dwordx4 v[52:55], v[26:27], off offset:16
	s_mov_b32 s12, 0x7fff7fff
	s_mov_b32 s15, 0x43700000
	s_waitcnt vmcnt(4)
	v_and_b32_e32 v64, s12, v32
	v_and_b32_e32 v68, s12, v33
	v_pk_max_u16 v64, v64, v68
	v_and_b32_e32 v68, s12, v34
	v_pk_max_u16 v64, v64, v68
	v_and_b32_e32 v68, s12, v35
	v_pk_max_u16 v64, v64, v68
	v_and_b32_e32 v68, s12, v36
	v_pk_max_u16 v64, v64, v68
	v_and_b32_e32 v68, s12, v37
	v_pk_max_u16 v64, v64, v68
	v_and_b32_e32 v68, s12, v38
	v_pk_max_u16 v64, v64, v68
	v_and_b32_e32 v68, s12, v39
	v_pk_max_u16 v64, v64, v68
	v_lshlrev_b32_e32 v68, 16, v64
	v_and_b32_e32 v64, 0xffff0000, v64
	v_max_u32_e32 v64, v64, v68
	s_waitcnt vmcnt(2)
	v_and_b32_e32 v65, s12, v40
	v_and_b32_e32 v69, s12, v41
	v_pk_max_u16 v65, v65, v69
	v_and_b32_e32 v69, s12, v42
	v_pk_max_u16 v65, v65, v69
	v_and_b32_e32 v69, s12, v43
	v_pk_max_u16 v65, v65, v69
	v_and_b32_e32 v69, s12, v44
	v_pk_max_u16 v65, v65, v69
	v_and_b32_e32 v69, s12, v45
	v_pk_max_u16 v65, v65, v69
	v_and_b32_e32 v69, s12, v46
	v_pk_max_u16 v65, v65, v69
	v_and_b32_e32 v69, s12, v47
	v_pk_max_u16 v65, v65, v69
	v_lshlrev_b32_e32 v69, 16, v65
	v_and_b32_e32 v65, 0xffff0000, v65
	v_max_u32_e32 v65, v65, v69
	s_waitcnt vmcnt(0)
	v_and_b32_e32 v66, s12, v48
	v_and_b32_e32 v70, s12, v49
	v_pk_max_u16 v66, v66, v70
	v_and_b32_e32 v70, s12, v50
	v_pk_max_u16 v66, v66, v70
	v_and_b32_e32 v70, s12, v51
	v_pk_max_u16 v66, v66, v70
	v_and_b32_e32 v70, s12, v52
	v_pk_max_u16 v66, v66, v70
	v_and_b32_e32 v70, s12, v53
	v_pk_max_u16 v66, v66, v70
	v_and_b32_e32 v70, s12, v54
	v_pk_max_u16 v66, v66, v70
	v_and_b32_e32 v70, s12, v55
	v_pk_max_u16 v66, v66, v70
	v_lshlrev_b32_e32 v70, 16, v66
	v_and_b32_e32 v66, 0xffff0000, v66
	v_max_u32_e32 v66, v66, v70
	ds_bpermute_b32 v68, v155, v64
	ds_bpermute_b32 v69, v155, v65
	ds_bpermute_b32 v70, v155, v66
	s_waitcnt lgkmcnt(2)
	v_max_u32_e32 v64, v64, v68
	s_waitcnt lgkmcnt(1)
	v_max_u32_e32 v65, v65, v69
	s_waitcnt lgkmcnt(0)
	v_max_u32_e32 v66, v66, v70
	ds_bpermute_b32 v68, v159, v64
	ds_bpermute_b32 v69, v159, v65
	ds_bpermute_b32 v70, v159, v66
	s_waitcnt lgkmcnt(2)
	v_max_u32_e32 v64, v64, v68
	s_waitcnt lgkmcnt(1)
	v_max_u32_e32 v65, v65, v69
	s_waitcnt lgkmcnt(0)
	v_max_u32_e32 v66, v66, v70
	ds_bpermute_b32 v68, v244, v64
	ds_bpermute_b32 v69, v244, v65
	ds_bpermute_b32 v70, v244, v66
	s_waitcnt lgkmcnt(2)
	v_max_u32_e32 v64, v64, v68
	s_waitcnt lgkmcnt(1)
	v_max_u32_e32 v65, v65, v69
	s_waitcnt lgkmcnt(0)
	v_max_u32_e32 v66, v66, v70
	ds_bpermute_b32 v68, v245, v64
	ds_bpermute_b32 v69, v245, v65
	ds_bpermute_b32 v70, v245, v66
	s_waitcnt lgkmcnt(2)
	v_max_u32_e32 v64, v64, v68
	s_waitcnt lgkmcnt(1)
	v_max_u32_e32 v65, v65, v69
	s_waitcnt lgkmcnt(0)
; __device__ __forceinline__ void ph_peer(const P& p, int l, int nrows, char* smem, int dryc) {
;     ...
;         am = fmaxf(am, __shfl_xor(am, 1, 64)); am = fmaxf(am, __shfl_xor(am, 2, 64)); am = fmaxf(am, __shfl_xor(am, 4, 64));
;         am = fmaxf(am, __shfl_xor(am, 8, 64)); am = fmaxf(am, __shfl_xor(am, 16, 64)); am = fmaxf(am, __shfl_xor(am, 32, 64));
;         float qs = am > 0.f ? 240.f / am : 1.f;
;         if (lane == 0) sQinv[wave * 4 + tk] = am > 0.f ? am * (1.f / 240.f) : 1.f;
;         u32x4 x8; int w;
; #pragma unroll
;         for (int i = 0; i < 4; i++) {
;           w = 0;
;           w = __builtin_amdgcn_cvt_pk_fp8_f32(xv[i * 4 + 0] * qs, xv[i * 4 + 1] * qs, w, false);
;           w = __builtin_amdgcn_cvt_pk_fp8_f32(xv[i * 4 + 2] * qs, xv[i * 4 + 3] * qs, w, true);
;           x8[i] = (u32)w;
;         }
;         *(u32x4*)(sX8 + (wave * 4 + tk) * 1024 + lane * 16) = x8;
	v_max_u32_e32 v66, v66, v70
	ds_bpermute_b32 v68, v246, v64
	ds_bpermute_b32 v69, v246, v65
	ds_bpermute_b32 v70, v246, v66
	s_waitcnt lgkmcnt(2)
	v_max_u32_e32 v64, v64, v68
	s_waitcnt lgkmcnt(1)
	v_max_u32_e32 v65, v65, v69
	s_waitcnt lgkmcnt(0)
	v_max_u32_e32 v66, v66, v70
	ds_bpermute_b32 v68, v247, v64
	ds_bpermute_b32 v69, v247, v65
	ds_bpermute_b32 v70, v247, v66
	s_waitcnt lgkmcnt(2)
	v_max_u32_e32 v64, v64, v68
	s_waitcnt lgkmcnt(1)
	v_max_u32_e32 v65, v65, v69
	s_waitcnt lgkmcnt(0)
	v_max_u32_e32 v66, v66, v70
	v_cmp_lt_f32_e64 s[12:13], 0, v64
	v_div_scale_f32 v72, s[0:1], v64, v64, s15
	v_rcp_f32_e32 v73, v72
	v_div_scale_f32 v74, vcc, s15, v64, s15
	v_fma_f32 v75, -v72, v73, 1.0
	v_fmac_f32_e32 v73, v75, v73
	v_mul_f32_e32 v75, v74, v73
	v_fma_f32 v76, -v72, v75, v74
	v_fmac_f32_e32 v75, v76, v73
	v_fma_f32 v72, -v72, v75, v74
	v_div_fmas_f32 v72, v72, v73, v75
	v_div_fixup_f32 v72, v72, v64, s15
	v_cndmask_b32_e64 v77, 1.0, v72, s[12:13]
	v_mul_f32_e32 v78, 0x3b888889, v64
	v_cndmask_b32_e64 v78, 1.0, v78, s[12:13]
	v_lshlrev_b32_e32 v68, 16, v32
	v_and_b32_e32 v69, 0xffff0000, v32
	v_lshlrev_b32_e32 v70, 16, v33
	v_and_b32_e32 v71, 0xffff0000, v33
	v_mul_f32_e32 v68, v77, v68
	v_mul_f32_e32 v69, v77, v69
	v_mul_f32_e32 v70, v77, v70
	v_mul_f32_e32 v71, v77, v71
	v_cvt_pk_fp8_f32 v84, v68, v69
	v_cvt_pk_fp8_f32 v84, v70, v71 op_sel:[0,0,1]
	v_lshlrev_b32_e32 v68, 16, v34
	v_and_b32_e32 v69, 0xffff0000, v34
	v_lshlrev_b32_e32 v70, 16, v35
	v_and_b32_e32 v71, 0xffff0000, v35
	v_mul_f32_e32 v68, v77, v68
	v_mul_f32_e32 v69, v77, v69
	v_mul_f32_e32 v70, v77, v70
	v_mul_f32_e32 v71, v77, v71
	v_cvt_pk_fp8_f32 v85, v68, v69
	v_cvt_pk_fp8_f32 v85, v70, v71 op_sel:[0,0,1]
	v_lshlrev_b32_e32 v68, 16, v36
	v_and_b32_e32 v69, 0xffff0000, v36
	v_lshlrev_b32_e32 v70, 16, v37
	v_and_b32_e32 v71, 0xffff0000, v37
	v_mul_f32_e32 v68, v77, v68
	v_mul_f32_e32 v69, v77, v69
	v_mul_f32_e32 v70, v77, v70
	v_mul_f32_e32 v71, v77, v71
	v_cvt_pk_fp8_f32 v86, v68, v69
	v_cvt_pk_fp8_f32 v86, v70, v71 op_sel:[0,0,1]
	v_lshlrev_b32_e32 v68, 16, v38
	v_and_b32_e32 v69, 0xffff0000, v38
	v_lshlrev_b32_e32 v70, 16, v39
	v_and_b32_e32 v71, 0xffff0000, v39
	v_mul_f32_e32 v68, v77, v68
	v_mul_f32_e32 v69, v77, v69
	v_mul_f32_e32 v70, v77, v70
	v_mul_f32_e32 v71, v77, v71
	v_cvt_pk_fp8_f32 v87, v68, v69
	v_cvt_pk_fp8_f32 v87, v70, v71 op_sel:[0,0,1]
	ds_write_b128 v2, v[84:87]
	s_and_saveexec_b64 s[0:1], s[10:11]
	ds_write_b32 v3, v78
	s_mov_b64 exec, s[0:1]
	v_cmp_lt_f32_e64 s[12:13], 0, v65
	v_div_scale_f32 v72, s[0:1], v65, v65, s15
	v_rcp_f32_e32 v73, v72
	v_div_scale_f32 v74, vcc, s15, v65, s15
	v_fma_f32 v75, -v72, v73, 1.0
	v_fmac_f32_e32 v73, v75, v73
	v_mul_f32_e32 v75, v74, v73
	v_fma_f32 v76, -v72, v75, v74
	v_fmac_f32_e32 v75, v76, v73
	v_fma_f32 v72, -v72, v75, v74
	v_div_fmas_f32 v72, v72, v73, v75
	v_div_fixup_f32 v72, v72, v65, s15
	v_cndmask_b32_e64 v77, 1.0, v72, s[12:13]
	v_mul_f32_e32 v78, 0x3b888889, v65
	v_cndmask_b32_e64 v78, 1.0, v78, s[12:13]
	v_lshlrev_b32_e32 v68, 16, v40
	v_and_b32_e32 v69, 0xffff0000, v40
	v_lshlrev_b32_e32 v70, 16, v41
	v_and_b32_e32 v71, 0xffff0000, v41
	v_mul_f32_e32 v68, v77, v68
	v_mul_f32_e32 v69, v77, v69
	v_mul_f32_e32 v70, v77, v70
	v_mul_f32_e32 v71, v77, v71
	v_cvt_pk_fp8_f32 v88, v68, v69
	v_cvt_pk_fp8_f32 v88, v70, v71 op_sel:[0,0,1]
	v_lshlrev_b32_e32 v68, 16, v42
	v_and_b32_e32 v69, 0xffff0000, v42
	v_lshlrev_b32_e32 v70, 16, v43
	v_and_b32_e32 v71, 0xffff0000, v43
	v_mul_f32_e32 v68, v77, v68
	v_mul_f32_e32 v69, v77, v69
	v_mul_f32_e32 v70, v77, v70
	v_mul_f32_e32 v71, v77, v71
	v_cvt_pk_fp8_f32 v89, v68, v69
	v_cvt_pk_fp8_f32 v89, v70, v71 op_sel:[0,0,1]
	v_lshlrev_b32_e32 v68, 16, v44
	v_and_b32_e32 v69, 0xffff0000, v44
	v_lshlrev_b32_e32 v70, 16, v45
	v_and_b32_e32 v71, 0xffff0000, v45
	v_mul_f32_e32 v68, v77, v68
	v_mul_f32_e32 v69, v77, v69
	v_mul_f32_e32 v70, v77, v70
	v_mul_f32_e32 v71, v77, v71
	v_cvt_pk_fp8_f32 v90, v68, v69
	v_cvt_pk_fp8_f32 v90, v70, v71 op_sel:[0,0,1]
	v_lshlrev_b32_e32 v68, 16, v46
	v_and_b32_e32 v69, 0xffff0000, v46
	v_lshlrev_b32_e32 v70, 16, v47
	v_and_b32_e32 v71, 0xffff0000, v47
	v_mul_f32_e32 v68, v77, v68
	v_mul_f32_e32 v69, v77, v69
	v_mul_f32_e32 v70, v77, v70
	v_mul_f32_e32 v71, v77, v71
	v_cvt_pk_fp8_f32 v91, v68, v69
	v_cvt_pk_fp8_f32 v91, v70, v71 op_sel:[0,0,1]
	ds_write_b128 v2, v[88:91] offset:1024
	s_and_saveexec_b64 s[0:1], s[10:11]
	ds_write_b32 v3, v78 offset:4
	s_mov_b64 exec, s[0:1]
	v_cmp_lt_f32_e64 s[12:13], 0, v66
	v_div_scale_f32 v72, s[0:1], v66, v66, s15
	v_rcp_f32_e32 v73, v72
	v_div_scale_f32 v74, vcc, s15, v66, s15
	v_fma_f32 v75, -v72, v73, 1.0
	v_fmac_f32_e32 v73, v75, v73
	v_mul_f32_e32 v75, v74, v73
	v_fma_f32 v76, -v72, v75, v74
	v_fmac_f32_e32 v75, v76, v73
	v_fma_f32 v72, -v72, v75, v74
	v_div_fmas_f32 v72, v72, v73, v75
	v_div_fixup_f32 v72, v72, v66, s15
	v_cndmask_b32_e64 v77, 1.0, v72, s[12:13]
	v_mul_f32_e32 v78, 0x3b888889, v66
	v_cndmask_b32_e64 v78, 1.0, v78, s[12:13]
	v_lshlrev_b32_e32 v68, 16, v48
	v_and_b32_e32 v69, 0xffff0000, v48
	v_lshlrev_b32_e32 v70, 16, v49
	v_and_b32_e32 v71, 0xffff0000, v49
	v_mul_f32_e32 v68, v77, v68
	v_mul_f32_e32 v69, v77, v69
	v_mul_f32_e32 v70, v77, v70
	v_mul_f32_e32 v71, v77, v71
	v_cvt_pk_fp8_f32 v92, v68, v69
	v_cvt_pk_fp8_f32 v92, v70, v71 op_sel:[0,0,1]
	v_lshlrev_b32_e32 v68, 16, v50
	v_and_b32_e32 v69, 0xffff0000, v50
	v_lshlrev_b32_e32 v70, 16, v51
	v_and_b32_e32 v71, 0xffff0000, v51
	v_mul_f32_e32 v68, v77, v68
	v_mul_f32_e32 v69, v77, v69
	v_mul_f32_e32 v70, v77, v70
	v_mul_f32_e32 v71, v77, v71
	v_cvt_pk_fp8_f32 v93, v68, v69
	v_cvt_pk_fp8_f32 v93, v70, v71 op_sel:[0,0,1]
	v_lshlrev_b32_e32 v68, 16, v52
	v_and_b32_e32 v69, 0xffff0000, v52
	v_lshlrev_b32_e32 v70, 16, v53
	v_and_b32_e32 v71, 0xffff0000, v53
	v_mul_f32_e32 v68, v77, v68
	v_mul_f32_e32 v69, v77, v69
	v_mul_f32_e32 v70, v77, v70
	v_mul_f32_e32 v71, v77, v71
	v_cvt_pk_fp8_f32 v94, v68, v69
	v_cvt_pk_fp8_f32 v94, v70, v71 op_sel:[0,0,1]
	v_lshlrev_b32_e32 v68, 16, v54
	v_and_b32_e32 v69, 0xffff0000, v54
	v_lshlrev_b32_e32 v70, 16, v55
	v_and_b32_e32 v71, 0xffff0000, v55
	v_mul_f32_e32 v68, v77, v68
	v_mul_f32_e32 v69, v77, v69
	v_mul_f32_e32 v70, v77, v70
	v_mul_f32_e32 v71, v77, v71
	v_cvt_pk_fp8_f32 v95, v68, v69
	v_cvt_pk_fp8_f32 v95, v70, v71 op_sel:[0,0,1]
	ds_write_b128 v2, v[92:95] offset:2048
	s_and_saveexec_b64 s[0:1], s[10:11]
	ds_write_b32 v3, v78 offset:8
	s_mov_b64 exec, s[0:1]

; __device__ __forceinline__ void ph_peer(const P& p, int l, int nrows, char* smem, int dryc) {
;     ...
;           const float* m = MOD + (size_t)(l * 9 + modrow_of(row)) * 6144;
;           float tt[16];
;           float* xr = xc + (size_t)row * 1024;
; #pragma unroll
;           for (int q = 0; q < 4; q++) {
;             int c = lane * 16 + q * 4;
;             float4 x4 = *(const float4*)(xr + c); float4 g5 = *(const float4*)(m + 5 * 1024 + c);
;             tt[q * 4 + 0] = ALPHA * x4.x + g5.x * f[q * 4 + 0];
;             tt[q * 4 + 1] = ALPHA * x4.y + g5.y * f[q * 4 + 1];
;             tt[q * 4 + 2] = ALPHA * x4.z + g5.z * f[q * 4 + 2];
;             tt[q * 4 + 3] = ALPHA * x4.w + g5.w * f[q * 4 + 3];
;           }
;           float sm = 0.f;
; #pragma unroll
;           for (int i = 0; i < 16; i++) sm += tt[i];
;           float mean = wave_sum(sm) * (1.f / 1024.f);
;           float ss = 0.f;
; #pragma unroll
;           for (int i = 0; i < 16; i++) { float dd = tt[i] - mean; ss += dd * dd; }
;           float rinv = rsqrtf(wave_sum(ss) * (1.f / 1024.f) + 1e-5f);
.LBB0_731:
	v_cndmask_b32_e64 v0, 0, 1, s[68:69]
	s_cmp_lt_u32 s18, s75
	v_lshlrev_b32_e32 v132, 2, v144
	v_cmp_ne_u32_e64 s[14:15], 1, v0
	s_cbranch_scc0 .LBB0_751
	v_add_u32_e32 v66, s18, v248
	v_min_i32_e32 v0, 0x4000, v66
	v_ashrrev_i32_e32 v38, 11, v0
	v_add_u32_e32 v0, s77, v38
	v_mul_hi_i32_i24_e32 v1, 0x6000, v0
	v_mul_i32_i24_e32 v0, 0x6000, v0
	v_lshl_add_u64 v[0:1], s[2:3], 0, v[0:1]
	v_lshl_add_u64 v[4:5], v[0:1], 0, v[132:133]
	s_mov_b64 s[0:1], 0x5000
	v_lshl_add_u64 v[12:13], v[4:5], 0, s[0:1]
	s_movk_i32 s0, 0x5000
	v_ashrrev_i32_e32 v67, 31, v66
	v_add_co_u32_e32 v8, vcc, s0, v4
	v_lshlrev_b64 v[16:17], 12, v[66:67]
	s_nop 0
	v_addc_co_u32_e32 v9, vcc, 0, v5, vcc
	v_lshl_add_u64 v[64:65], v[150:151], 0, v[16:17]
	global_load_dwordx4 v[0:3], v[12:13], off offset:48
	global_load_dwordx4 v[4:7], v[12:13], off offset:32
	s_nop 0
	global_load_dwordx4 v[8:11], v[8:9], off
	s_nop 0
	global_load_dwordx4 v[12:15], v[12:13], off offset:16
	s_nop 0
	global_load_dwordx4 v[16:19], v[64:65], off offset:48
	global_load_dwordx4 v[20:23], v[64:65], off offset:32
	global_load_dwordx4 v[24:27], v[64:65], off offset:16
	global_load_dwordx4 v[28:31], v[64:65], off
	s_mov_b32 s0, 0x3fd744fd
	v_mov_b64_e32 v[36:37], s[2:3]
	s_waitcnt vmcnt(6)
	v_pk_mul_f32 v[4:5], v[198:199], v[4:5]
	s_waitcnt vmcnt(5)
	v_pk_mul_f32 v[8:9], v[200:201], v[8:9]
	v_pk_mul_f32 v[0:1], v[194:195], v[0:1]
	s_waitcnt vmcnt(0)
	v_pk_fma_f32 v[80:81], v[28:29], s[0:1], v[8:9] op_sel_hi:[1,0,1]
	v_pk_mul_f32 v[10:11], v[192:193], v[10:11]
	v_pk_fma_f32 v[68:69], v[16:17], s[0:1], v[0:1] op_sel_hi:[1,0,1]
	v_add_f32_e32 v0, 0, v80
	v_pk_fma_f32 v[82:83], v[30:31], s[0:1], v[10:11] op_sel_hi:[1,0,1]
	v_add_f32_e32 v0, v0, v81
	v_pk_mul_f32 v[12:13], v[202:203], v[12:13]
	v_add_f32_e32 v0, v0, v82
	v_pk_fma_f32 v[76:77], v[24:25], s[0:1], v[12:13] op_sel_hi:[1,0,1]
	v_add_f32_e32 v0, v0, v83
	v_pk_mul_f32 v[14:15], v[196:197], v[14:15]
	v_add_f32_e32 v0, v0, v76
	v_pk_fma_f32 v[78:79], v[26:27], s[0:1], v[14:15] op_sel_hi:[1,0,1]
	v_add_f32_e32 v0, v0, v77
	v_add_f32_e32 v0, v0, v78
	v_pk_fma_f32 v[72:73], v[20:21], s[0:1], v[4:5] op_sel_hi:[1,0,1]
	v_add_f32_e32 v0, v0, v79
	v_pk_mul_f32 v[6:7], v[190:191], v[6:7]
	v_add_f32_e32 v0, v0, v72
	v_pk_fma_f32 v[74:75], v[22:23], s[0:1], v[6:7] op_sel_hi:[1,0,1]
	v_add_f32_e32 v0, v0, v73
	v_add_f32_e32 v0, v0, v74
	v_add_f32_e32 v0, v0, v75
	v_pk_mul_f32 v[2:3], v[188:189], v[2:3]
	v_add_f32_e32 v0, v0, v68
	v_pk_fma_f32 v[70:71], v[18:19], s[0:1], v[2:3] op_sel_hi:[1,0,1]
	v_add_f32_e32 v0, v0, v69
	v_add_f32_e32 v0, v0, v70
	v_add_f32_e32 v4, v0, v71
	s_movk_i32 s0, 0x6000
	global_load_dwordx4 v[0:3], v[146:147], off offset:48
	global_load_dwordx4 v[16:19], v[146:147], off offset:32
	global_load_dwordx4 v[32:35], v[146:147], off offset:16
	global_load_dwordx4 v[48:51], v[146:147], off
	global_load_dwordx4 v[8:11], v[148:149], off offset:48
	global_load_dwordx4 v[24:27], v[148:149], off offset:32
	global_load_dwordx4 v[40:43], v[148:149], off offset:16
	global_load_dwordx4 v[56:59], v[148:149], off
	s_nop 1
	v_add_f32_dpp v4, v4, v4 quad_perm:[1,0,3,2] row_mask:0xf bank_mask:0xf
	s_nop 1
	v_add_f32_dpp v6, v4, v4 quad_perm:[2,3,0,1] row_mask:0xf bank_mask:0xf
	v_add_u32_e32 v4, s78, v38
	v_mad_i64_i32 v[4:5], s[0:1], v4, s0, v[36:37]
	v_lshl_add_u64 v[12:13], v[4:5], 0, v[132:133]
	s_nop 1
	v_add_f32_dpp v14, v6, v6 row_half_mirror row_mask:0xf bank_mask:0xf
	s_mov_b64 s[0:1], 0x1000
	v_lshl_add_u64 v[44:45], v[12:13], 0, s[0:1]
	s_movk_i32 s0, 0x1000
	global_load_dwordx4 v[4:7], v[12:13], off offset:48
	global_load_dwordx4 v[20:23], v[12:13], off offset:32
	global_load_dwordx4 v[36:39], v[12:13], off offset:16
	global_load_dwordx4 v[52:55], v[12:13], off
	s_nop 1
	v_add_f32_dpp v14, v14, v14 row_mirror row_mask:0xf bank_mask:0xf
	v_add_co_u32_e32 v12, vcc, s0, v12
	s_mov_b32 s0, 0x800000
	s_nop 0
	v_addc_co_u32_e32 v13, vcc, 0, v13, vcc
	v_mov_b32_e32 v15, v14
	v_mov_b32_e32 v84, v14
	s_nop 1
	v_permlane16_swap_b32_e32 v84, v15
	v_add_f32_e32 v84, v84, v15
	global_load_dwordx4 v[60:63], v[12:13], off
	s_nop 0
	global_load_dwordx4 v[12:15], v[44:45], off offset:48
	global_load_dwordx4 v[28:31], v[44:45], off offset:32
	s_nop 0
	global_load_dwordx4 v[44:47], v[44:45], off offset:16
	v_mov_b32_e32 v85, v84
	s_nop 1
	v_permlane32_swap_b32_e32 v84, v85
	v_add_f32_e32 v84, v84, v85
	v_mul_f32_e32 v88, 0x3a800000, v84
	v_pk_add_f32 v[84:85], v[80:81], v[88:89] op_sel_hi:[1,0] neg_lo:[0,1] neg_hi:[0,1]
	v_pk_add_f32 v[86:87], v[82:83], v[88:89] op_sel_hi:[1,0] neg_lo:[0,1] neg_hi:[0,1]
	v_pk_add_f32 v[80:81], v[78:79], v[88:89] op_sel_hi:[1,0] neg_lo:[0,1] neg_hi:[0,1]
	v_pk_add_f32 v[78:79], v[72:73], v[88:89] op_sel_hi:[1,0] neg_lo:[0,1] neg_hi:[0,1]
	v_pk_add_f32 v[72:73], v[68:69], v[88:89] op_sel_hi:[1,0] neg_lo:[0,1] neg_hi:[0,1]
	v_pk_mul_f32 v[68:69], v[84:85], v[84:85]
	v_pk_add_f32 v[82:83], v[76:77], v[88:89] op_sel_hi:[1,0] neg_lo:[0,1] neg_hi:[0,1]
	v_pk_add_f32 v[76:77], v[74:75], v[88:89] op_sel_hi:[1,0] neg_lo:[0,1] neg_hi:[0,1]
	v_pk_mul_f32 v[74:75], v[86:87], v[86:87]
	v_add_f32_e32 v68, v68, v69
	v_add_f32_e32 v68, v74, v68
	v_pk_add_f32 v[70:71], v[70:71], v[88:89] op_sel_hi:[1,0] neg_lo:[0,1] neg_hi:[0,1]
	v_pk_mul_f32 v[88:89], v[82:83], v[82:83]
	v_add_f32_e32 v68, v75, v68
	v_add_f32_e32 v68, v88, v68
	v_pk_mul_f32 v[90:91], v[80:81], v[80:81]
	v_add_f32_e32 v68, v89, v68
	v_add_f32_e32 v68, v90, v68
	v_pk_mul_f32 v[92:93], v[78:79], v[78:79]
	v_add_f32_e32 v68, v91, v68
	v_add_f32_e32 v68, v92, v68
	v_pk_mul_f32 v[94:95], v[76:77], v[76:77]
	v_add_f32_e32 v68, v93, v68
	v_add_f32_e32 v68, v94, v68
	v_pk_mul_f32 v[96:97], v[72:73], v[72:73]
	v_add_f32_e32 v68, v95, v68
	v_add_f32_e32 v68, v96, v68
	v_pk_mul_f32 v[98:99], v[70:71], v[70:71]
	v_add_f32_e32 v68, v97, v68
	v_add_f32_e32 v68, v98, v68
	v_add_f32_e32 v68, v99, v68
	s_nop 1
	v_add_f32_dpp v68, v68, v68 quad_perm:[1,0,3,2] row_mask:0xf bank_mask:0xf
	s_nop 1
	v_add_f32_dpp v68, v68, v68 quad_perm:[2,3,0,1] row_mask:0xf bank_mask:0xf
	s_nop 1
	v_add_f32_dpp v68, v68, v68 row_half_mirror row_mask:0xf bank_mask:0xf
	s_nop 1
	v_add_f32_dpp v68, v68, v68 row_mirror row_mask:0xf bank_mask:0xf
	v_mov_b32_e32 v69, v68
	s_nop 1
	v_permlane16_swap_b32_e32 v68, v69
	v_add_f32_e32 v68, v68, v69
	v_mov_b32_e32 v69, v68
	s_nop 1
	v_permlane32_swap_b32_e32 v68, v69
	v_add_f32_e32 v68, v68, v69
	v_fmamk_f32 v68, v68, 0x3a800000, v139
	v_mul_f32_e32 v69, 0x4b800000, v68
	v_cmp_gt_f32_e32 vcc, s0, v68
	s_nop 1
	v_cndmask_b32_e32 v68, v68, v69, vcc
	v_rsq_f32_e32 v74, v68
	v_lshlrev_b64 v[68:69], 10, v[66:67]
	v_lshlrev_b64 v[66:67], 11, v[66:67]
	v_lshl_add_u64 v[66:67], s[56:57], 0, v[66:67]
	v_mul_f32_e32 v75, 0x45800000, v74
	v_cndmask_b32_e32 v74, v74, v75, vcc
	s_and_b64 vcc, exec, s[14:15]
	v_mov_b32_e32 v75, v74
	s_cbranch_vccnz .LBB0_741
; __device__ __forceinline__ void ph_peer(const P& p, int l, int nrows, char* smem, int dryc) {
;     ...
; #pragma unroll
;           for (int q = 0; q < 4; q++) {
;             int c = lane * 16 + q * 4;
;             float4 y;
;             y.x = (tt[q * 4 + 0] - mean) * rinv * gg4[q][0] + bb4[q][0];
;             y.y = (tt[q * 4 + 1] - mean) * rinv * gg4[q][1] + bb4[q][1];
;             y.z = (tt[q * 4 + 2] - mean) * rinv * gg4[q][2] + bb4[q][2];
;             y.w = (tt[q * 4 + 3] - mean) * rinv * gg4[q][3] + bb4[q][3];
;             if (dry) {
;             } else if (l == 3) {
;               *(float4*)(p.out + (size_t)row * 1024 + c) = y;
;             } else {
;               *(float4*)(xr + c) = y;
;               uint2 o; o.x = pack2(y.x * (1.f + sc4[q][0]) + sh4[q][0], y.y * (1.f + sc4[q][1]) + sh4[q][1]);
;               o.y = pack2(y.z * (1.f + sc4[q][2]) + sh4[q][2], y.w * (1.f + sc4[q][3]) + sh4[q][3]);
;               *(uint2*)(xm + (size_t)row * 1024 + c) = o;
;             }
	v_pk_mul_f32 v[84:85], v[84:85], v[74:75]
	s_mov_b64 s[0:1], -1
	s_waitcnt vmcnt(8)
	v_pk_fma_f32 v[48:49], v[48:49], v[84:85], v[56:57]
	v_pk_mul_f32 v[56:57], v[86:87], v[74:75]
	s_and_b64 vcc, exec, s[66:67]
	v_pk_fma_f32 v[50:51], v[50:51], v[56:57], v[58:59]
	s_cbranch_vccz .LBB0_735
	s_waitcnt vmcnt(3)
	v_pk_add_f32 v[56:57], v[60:61], 1.0 op_sel_hi:[1,0]
	global_store_dwordx4 v[64:65], v[48:51], off
	v_pk_fma_f32 v[52:53], v[56:57], v[48:49], v[52:53]
	v_pk_add_f32 v[56:57], v[62:63], 1.0 op_sel_hi:[1,0]
	v_cvt_pk_bf16_f32 v52, v52, v53
	v_pk_fma_f32 v[54:55], v[56:57], v[50:51], v[54:55]
	s_mov_b64 s[0:1], 0
	v_cvt_pk_bf16_f32 v53, v54, v55
	v_lshlrev_b32_e32 v54, 1, v144
	v_mov_b32_e32 v55, v133
	v_lshl_add_u64 v[54:55], v[66:67], 0, v[54:55]
	global_store_dwordx2 v[54:55], v[52:53], off
